# GEMM K-loops of the up/down projections: the leading wave group waits for its LDS-DMA loads after its MFMA section instead of before the opening barrier
# baseline (speedup 1.0000x reference)
.LBB0_1070:
	s_ashr_i32 s0, s7, 3
	s_add_u32 s40, s78, 0x30000000
	v_lshrrev_b32_e32 v3, 1, v153
	s_addc_u32 s41, s79, 0
	v_and_b32_e32 v13, 24, v3
	v_lshrrev_b32_e32 v3, 5, v153
	s_add_u32 s42, s78, 0x2e00000
	v_and_b32_e32 v3, 4, v3
	v_bfe_u32 v4, v153, 2, 2
	s_addc_u32 s43, s79, 0
	v_lshlrev_b32_e32 v1, 4, v153
	v_and_b32_e32 v2, 32, v153
	v_bfe_u32 v12, v153, 2, 4
	v_or3_b32 v3, v3, v4, v13
	v_lshrrev_b32_e32 v4, 3, v153
	s_movk_i32 s7, 0x70
	s_add_i32 s0, s6, s0
	v_bitop3_b32 v10, v1, v2, 48 bitop3:0x6c
	v_and_b32_e32 v11, 64, v153
	v_and_or_b32 v5, v4, s7, v12
	s_movk_i32 s7, 0x60
	v_add_u32_e32 v14, 0x2000, v1
	s_ashr_i32 s6, s0, 31
	v_or_b32_e32 v2, v10, v11
	v_and_or_b32 v4, v4, s7, v3
	v_lshrrev_b32_e32 v1, 7, v14
	s_movk_i32 s7, 0xf0
	s_lshr_b32 s6, s6, 24
	v_lshl_or_b32 v132, v4, 12, v2
	v_and_or_b32 v4, v1, s7, v12
	s_movk_i32 s7, 0xe0
	s_add_i32 s6, s0, s6
	v_and_or_b32 v1, v1, s7, v3
	s_ashr_i32 s7, s6, 8
	s_and_b32 s6, s6, 0xffffff00
	s_sub_i32 s6, s0, s6
	s_sext_i32_i16 s0, s6
	s_bfe_u32 s0, s0, 0x3001c
	s_add_i32 s8, s6, s0
	s_sext_i32_i16 s0, s8
	s_and_b32 s8, s8, 0xfff8
	s_sub_i32 s6, s6, s8
	s_lshl_b32 s7, s7, 3
	s_sext_i32_i16 s6, s6
	s_lshr_b32 s1, s12, 8
	s_lshr_b32 s0, s0, 3
	s_add_i32 s30, s7, s6
	s_lshr_b32 s10, s12, 6
	s_ashr_i32 s31, s30, 31
	s_bfe_i64 s[8:9], s[0:1], 0x100000
	s_lshl_b32 s44, s10, 10
	s_lshl_b64 s[6:7], s[30:31], 20
	s_lshl_b64 s[8:9], s[8:9], 20
	s_add_u32 s36, s42, s8
	s_addc_u32 s37, s43, s9
	s_add_i32 s31, s44, 0
	s_add_i32 m0, s31, 0x10000
	v_lshl_or_b32 v136, v1, 12, v2
	global_load_lds_dwordx4 v132, s[36:37]
	s_add_i32 m0, s31, 0x12000
	s_add_u32 s8, s36, 0x80000
	global_load_lds_dwordx4 v136, s[36:37]
	s_addc_u32 s9, s37, 0
	s_add_i32 m0, s31, 0x14000
	v_lshl_or_b32 v130, v5, 12, v2
	global_load_lds_dwordx4 v132, s[8:9]
	s_add_i32 m0, s31, 0x16000
	s_add_u32 s34, s40, s6
	s_addc_u32 s35, s41, s7
	s_add_i32 s45, s31, 0x2000
	global_load_lds_dwordx4 v136, s[8:9]
	s_mov_b32 m0, s31
	s_add_u32 s6, s34, 0x80000
	v_lshl_or_b32 v134, v4, 12, v2
	global_load_lds_dwordx4 v130, s[34:35]
	s_mov_b32 m0, s45
	s_addc_u32 s7, s35, 0
	s_add_i32 s46, s31, 0x4000
	global_load_lds_dwordx4 v134, s[34:35]
	s_mov_b32 m0, s46
	s_add_i32 s47, s31, 0x6000
	global_load_lds_dwordx4 v130, s[6:7]
	s_mov_b32 m0, s47
	v_mov_b32_e32 v133, 0
	global_load_lds_dwordx4 v134, s[6:7]
	v_mov_b32_e32 v137, v133
	v_mov_b32_e32 v131, v133
	v_mov_b32_e32 v135, v133
	s_cmp_eq_u32 s1, 1
	s_mov_b32 s48, 0
	v_lshl_add_u64 v[8:9], s[36:37], 0, v[132:133]
	v_lshl_add_u64 v[6:7], s[36:37], 0, v[136:137]
	v_lshl_add_u64 v[2:3], s[34:35], 0, v[130:131]
	s_cselect_b64 s[6:7], -1, 0
	s_mov_b32 s87, s1
	s_cmp_lg_u32 s1, 1
	v_lshl_add_u64 v[4:5], s[34:35], 0, v[134:135]
	s_cbranch_scc1 .LBB0_1072
	s_barrier

.LBB0_1082:
	ds_read_b128 v[156:159], v151
	ds_read_b128 v[160:163], v151 offset:1024
	ds_read_b128 v[164:167], v151 offset:2048
	ds_read_b128 v[168:171], v151 offset:3072
	ds_read_b128 v[172:175], v154
	ds_read_b128 v[176:179], v154 offset:1024
	ds_read_b128 v[180:183], v154 offset:2048
	ds_read_b128 v[184:187], v154 offset:3072
	s_add_u32 s36, s34, 0xfff80080
	s_addc_u32 s37, s35, -1
	s_cmp_eq_u32 s63, 28
	s_cselect_b32 s39, s25, s37
	s_cselect_b32 s38, s59, s36
	s_cselect_b32 s37, s23, s62
	s_cselect_b32 s36, s60, s61
	v_lshl_add_u64 v[146:147], s[34:35], 0, v[138:139]
	s_add_i32 m0, s31, 0xc000
	ds_read_b128 v[188:191], v155
	ds_read_b128 v[192:195], v155 offset:1024
	ds_read_b128 v[196:199], v155 offset:2048
	ds_read_b128 v[200:203], v155 offset:3072
	ds_read_b128 v[204:207], v155 offset:4096
	ds_read_b128 v[208:211], v155 offset:5120
	ds_read_b128 v[212:215], v155 offset:6144
	ds_read_b128 v[216:219], v155 offset:7168
	global_load_lds_dwordx4 v[146:147], off
	v_lshl_add_u64 v[146:147], s[34:35], 0, v[140:141]
	s_add_i32 m0, s31, 0xe000
	s_nop 0
	global_load_lds_dwordx4 v[146:147], off
	s_cmp_eq_u32 s87, 0
	s_cbranch_scc1 .Lgw9_0a
	s_waitcnt vmcnt(8)
.Lgw9_0a:
	s_waitcnt lgkmcnt(0)
	s_barrier
	s_setprio 1
	s_waitcnt lgkmcnt(0)
	v_mfma_f32_16x16x32_bf16 v[126:129], v[156:159], v[188:191], v[126:129]
	v_mfma_f32_16x16x32_bf16 v[122:125], v[164:167], v[188:191], v[122:125]
	v_mfma_f32_16x16x32_bf16 v[110:113], v[156:159], v[196:199], v[110:113]
	v_mfma_f32_16x16x32_bf16 v[106:109], v[164:167], v[196:199], v[106:109]
	v_mfma_f32_16x16x32_bf16 v[94:97], v[156:159], v[204:207], v[94:97]
	v_mfma_f32_16x16x32_bf16 v[90:93], v[164:167], v[204:207], v[90:93]
	v_mfma_f32_16x16x32_bf16 v[78:81], v[156:159], v[212:215], v[78:81]
	v_mfma_f32_16x16x32_bf16 v[74:77], v[164:167], v[212:215], v[74:77]
	v_mfma_f32_16x16x32_bf16 v[126:129], v[160:163], v[192:195], v[126:129]
	v_mfma_f32_16x16x32_bf16 v[122:125], v[168:171], v[192:195], v[122:125]
	v_mfma_f32_16x16x32_bf16 v[110:113], v[160:163], v[200:203], v[110:113]
	v_mfma_f32_16x16x32_bf16 v[106:109], v[168:171], v[200:203], v[106:109]
	v_mfma_f32_16x16x32_bf16 v[94:97], v[160:163], v[208:211], v[94:97]
	v_mfma_f32_16x16x32_bf16 v[90:93], v[168:171], v[208:211], v[90:93]
	v_mfma_f32_16x16x32_bf16 v[78:81], v[160:163], v[216:219], v[78:81]
	v_mfma_f32_16x16x32_bf16 v[74:77], v[168:171], v[216:219], v[74:77]
	s_setprio 0
	s_setprio 1
	v_mfma_f32_16x16x32_bf16 v[118:121], v[172:175], v[188:191], v[118:121]
	v_mfma_f32_16x16x32_bf16 v[114:117], v[180:183], v[188:191], v[114:117]
	v_mfma_f32_16x16x32_bf16 v[102:105], v[172:175], v[196:199], v[102:105]
	v_mfma_f32_16x16x32_bf16 v[98:101], v[180:183], v[196:199], v[98:101]
	v_mfma_f32_16x16x32_bf16 v[86:89], v[172:175], v[204:207], v[86:89]
	v_mfma_f32_16x16x32_bf16 v[82:85], v[180:183], v[204:207], v[82:85]
	v_mfma_f32_16x16x32_bf16 v[70:73], v[172:175], v[212:215], v[70:73]
	v_mfma_f32_16x16x32_bf16 v[66:69], v[180:183], v[212:215], v[66:69]
	v_mfma_f32_16x16x32_bf16 v[118:121], v[176:179], v[192:195], v[118:121]
	v_mfma_f32_16x16x32_bf16 v[114:117], v[184:187], v[192:195], v[114:117]
	v_mfma_f32_16x16x32_bf16 v[102:105], v[176:179], v[200:203], v[102:105]
	v_mfma_f32_16x16x32_bf16 v[98:101], v[184:187], v[200:203], v[98:101]
	v_mfma_f32_16x16x32_bf16 v[86:89], v[176:179], v[208:211], v[86:89]
	v_mfma_f32_16x16x32_bf16 v[82:85], v[184:187], v[208:211], v[82:85]
	v_mfma_f32_16x16x32_bf16 v[70:73], v[176:179], v[216:219], v[70:73]
	v_mfma_f32_16x16x32_bf16 v[66:69], v[184:187], v[216:219], v[66:69]
	s_setprio 0
	s_cbranch_scc0 .Lgw9_0b
	s_waitcnt vmcnt(8)
.Lgw9_0b:
	s_barrier
	s_add_i32 s64, s52, s44
	v_lshl_add_u64 v[146:147], s[36:37], 0, v[132:133]
	s_mov_b32 m0, s64
	ds_read_b128 v[188:191], v155 offset:16384
	ds_read_b128 v[192:195], v155 offset:17408
	ds_read_b128 v[196:199], v155 offset:18432
	ds_read_b128 v[200:203], v155 offset:19456
	ds_read_b128 v[204:207], v155 offset:20480
	ds_read_b128 v[208:211], v155 offset:21504
	ds_read_b128 v[212:215], v155 offset:22528
	ds_read_b128 v[216:219], v155 offset:23552
	global_load_lds_dwordx4 v[146:147], off
	s_add_i32 m0, s64, 0x2000
	s_add_u32 s64, s36, 0x80000
	v_lshl_add_u64 v[220:221], s[36:37], 0, v[136:137]
	s_addc_u32 s65, s37, 0
	s_add_i32 s66, s53, s44
	global_load_lds_dwordx4 v[220:221], off
	v_lshl_add_u64 v[222:223], s[64:65], 0, v[132:133]
	s_mov_b32 m0, s66
	v_lshl_add_u64 v[224:225], s[38:39], 0, v[134:135]
	global_load_lds_dwordx4 v[222:223], off
	v_lshl_add_u64 v[222:223], s[64:65], 0, v[136:137]
	s_add_i32 m0, s66, 0x2000
	s_nop 0
	global_load_lds_dwordx4 v[222:223], off
	v_lshl_add_u64 v[222:223], s[38:39], 0, v[130:131]
	s_mov_b32 m0, s31
	s_nop 0
	global_load_lds_dwordx4 v[222:223], off
	s_mov_b32 m0, s45
	s_nop 0
	global_load_lds_dwordx4 v[224:225], off
	s_cmp_eq_u32 s87, 0
	s_cbranch_scc1 .Lgw9_1a
	s_waitcnt vmcnt(8)
.Lgw9_1a:
	s_waitcnt lgkmcnt(0)
	s_barrier
	s_setprio 1
	s_waitcnt lgkmcnt(0)
	v_mfma_f32_16x16x32_bf16 v[62:65], v[156:159], v[188:191], v[62:65]
	v_mfma_f32_16x16x32_bf16 v[58:61], v[164:167], v[188:191], v[58:61]
	v_mfma_f32_16x16x32_bf16 v[46:49], v[156:159], v[196:199], v[46:49]
	v_mfma_f32_16x16x32_bf16 v[42:45], v[164:167], v[196:199], v[42:45]
	v_mfma_f32_16x16x32_bf16 v[30:33], v[156:159], v[204:207], v[30:33]
	v_mfma_f32_16x16x32_bf16 v[26:29], v[164:167], v[204:207], v[26:29]
	v_mfma_f32_16x16x32_bf16 v[14:17], v[156:159], v[212:215], v[14:17]
	v_mfma_f32_16x16x32_bf16 v[10:13], v[164:167], v[212:215], v[10:13]
	v_mfma_f32_16x16x32_bf16 v[62:65], v[160:163], v[192:195], v[62:65]
	v_mfma_f32_16x16x32_bf16 v[58:61], v[168:171], v[192:195], v[58:61]
	v_mfma_f32_16x16x32_bf16 v[46:49], v[160:163], v[200:203], v[46:49]
	v_mfma_f32_16x16x32_bf16 v[42:45], v[168:171], v[200:203], v[42:45]
	v_mfma_f32_16x16x32_bf16 v[30:33], v[160:163], v[208:211], v[30:33]
	v_mfma_f32_16x16x32_bf16 v[26:29], v[168:171], v[208:211], v[26:29]
	v_mfma_f32_16x16x32_bf16 v[14:17], v[160:163], v[216:219], v[14:17]
	v_mfma_f32_16x16x32_bf16 v[10:13], v[168:171], v[216:219], v[10:13]
	s_setprio 0
	s_setprio 1
	v_mfma_f32_16x16x32_bf16 v[54:57], v[172:175], v[188:191], v[54:57]
	v_mfma_f32_16x16x32_bf16 v[50:53], v[180:183], v[188:191], v[50:53]
	v_mfma_f32_16x16x32_bf16 v[38:41], v[172:175], v[196:199], v[38:41]
	v_mfma_f32_16x16x32_bf16 v[34:37], v[180:183], v[196:199], v[34:37]
	v_mfma_f32_16x16x32_bf16 v[22:25], v[172:175], v[204:207], v[22:25]
	v_mfma_f32_16x16x32_bf16 v[18:21], v[180:183], v[204:207], v[18:21]
	v_mfma_f32_16x16x32_bf16 v[6:9], v[172:175], v[212:215], v[6:9]
	v_mfma_f32_16x16x32_bf16 v[2:5], v[180:183], v[212:215], v[2:5]
	v_mfma_f32_16x16x32_bf16 v[54:57], v[176:179], v[192:195], v[54:57]
	v_mfma_f32_16x16x32_bf16 v[50:53], v[184:187], v[192:195], v[50:53]
	v_mfma_f32_16x16x32_bf16 v[38:41], v[176:179], v[200:203], v[38:41]
	v_mfma_f32_16x16x32_bf16 v[34:37], v[184:187], v[200:203], v[34:37]
	v_mfma_f32_16x16x32_bf16 v[22:25], v[176:179], v[208:211], v[22:25]
	v_mfma_f32_16x16x32_bf16 v[18:21], v[184:187], v[208:211], v[18:21]
	v_mfma_f32_16x16x32_bf16 v[6:9], v[176:179], v[216:219], v[6:9]
	v_mfma_f32_16x16x32_bf16 v[2:5], v[184:187], v[216:219], v[2:5]
	s_setprio 0
	s_cbranch_scc0 .Lgw9_1b
	s_waitcnt vmcnt(8)
.Lgw9_1b:
	s_barrier
	s_add_i32 s64, 0, 0x18000
	s_add_i32 s65, 0, 0x1c000
	v_add_u32_e32 v168, s64, v149
	v_add_u32_e32 v184, s65, v149
	ds_read_b128 v[156:159], v168
	ds_read_b128 v[160:163], v168 offset:1024
	ds_read_b128 v[164:167], v168 offset:2048
	ds_read_b128 v[168:171], v168 offset:3072
	ds_read_b128 v[172:175], v184
	ds_read_b128 v[176:179], v184 offset:1024
	ds_read_b128 v[180:183], v184 offset:2048
	ds_read_b128 v[184:187], v184 offset:3072
	s_add_u32 s38, s38, 0x80000
	s_addc_u32 s39, s39, 0
	s_mov_b32 m0, s46
	v_lshl_add_u64 v[226:227], s[38:39], 0, v[130:131]
	ds_read_b128 v[188:191], v155 offset:32768
	ds_read_b128 v[192:195], v155 offset:33792
	ds_read_b128 v[196:199], v155 offset:34816
	ds_read_b128 v[200:203], v155 offset:35840
	ds_read_b128 v[204:207], v155 offset:36864
	ds_read_b128 v[208:211], v155 offset:37888
	ds_read_b128 v[212:215], v155 offset:38912
	ds_read_b128 v[216:219], v155 offset:39936
	global_load_lds_dwordx4 v[226:227], off
	v_lshl_add_u64 v[226:227], s[38:39], 0, v[134:135]
	s_mov_b32 m0, s47
	s_nop 0
	global_load_lds_dwordx4 v[226:227], off
	s_cmp_eq_u32 s87, 0
	s_cbranch_scc1 .Lgw9_2a
	s_waitcnt vmcnt(8)

.Lgw9_2b:
	s_barrier
	s_add_i32 s38, s64, s44
	v_lshl_add_u64 v[146:147], v[146:147], 0, s[10:11]
	s_mov_b32 m0, s38
	ds_read_b128 v[188:191], v155 offset:49152
	ds_read_b128 v[192:195], v155 offset:50176
	ds_read_b128 v[196:199], v155 offset:51200
	ds_read_b128 v[200:203], v155 offset:52224
	ds_read_b128 v[204:207], v155 offset:53248
	ds_read_b128 v[208:211], v155 offset:54272
	ds_read_b128 v[212:215], v155 offset:55296
	ds_read_b128 v[216:219], v155 offset:56320
	global_load_lds_dwordx4 v[146:147], off
	s_add_i32 m0, s38, 0x2000
	s_add_u32 s36, s36, 0x80080
	v_lshl_add_u64 v[146:147], v[220:221], 0, s[10:11]
	s_addc_u32 s37, s37, 0
	s_add_i32 s38, s65, s44
	global_load_lds_dwordx4 v[146:147], off
	v_lshl_add_u64 v[146:147], s[36:37], 0, v[132:133]
	s_mov_b32 m0, s38
	s_nop 0
	global_load_lds_dwordx4 v[146:147], off
	v_lshl_add_u64 v[146:147], s[36:37], 0, v[136:137]
	s_add_i32 m0, s38, 0x2000
	s_nop 0
	global_load_lds_dwordx4 v[146:147], off
	v_lshl_add_u64 v[146:147], v[222:223], 0, s[10:11]
	s_mov_b32 m0, s49
	s_nop 0
	global_load_lds_dwordx4 v[146:147], off
	v_lshl_add_u64 v[146:147], v[224:225], 0, s[10:11]
	s_mov_b32 m0, s50
	s_nop 0
	global_load_lds_dwordx4 v[146:147], off
	s_cmp_eq_u32 s87, 0
	s_cbranch_scc1 .Lgw9_3a
	s_waitcnt vmcnt(8)

.Lgw9_3b:
	s_barrier
	s_add_i32 s63, s63, 2
	s_add_u32 s34, s34, 0x100
	s_addc_u32 s35, s35, 0
	s_add_u32 s61, s61, 0x100
	s_addc_u32 s62, s62, 0
	s_cmp_gt_u32 s63, 29
	s_cbranch_scc0 .LBB0_1082
	s_and_b64 vcc, exec, s[12:13]
	s_cbranch_vccz .LBB0_1085
	s_barrier

.LBB0_1178:
	s_add_u32 s40, s78, 0xf000000
	s_addc_u32 s41, s79, 0
	s_add_u32 s42, s78, 0x4e00000
	s_addc_u32 s43, s79, 0
	s_add_i32 s0, s6, s0
	s_ashr_i32 s6, s0, 31
	s_lshr_b32 s6, s6, 26
	s_add_i32 s6, s0, s6
	s_ashr_i32 s7, s6, 6
	s_and_b32 s6, s6, 0xffc0
	v_lshrrev_b32_e32 v3, 1, v153
	s_sub_i32 s6, s0, s6
	v_and_b32_e32 v13, 24, v3
	v_lshrrev_b32_e32 v3, 5, v153
	s_bfe_i32 s0, s6, 0x80000
	v_and_b32_e32 v3, 4, v3
	v_bfe_u32 v4, v153, 2, 2
	s_bfe_u32 s0, s0, 0x3000c
	v_lshlrev_b32_e32 v1, 4, v153
	v_and_b32_e32 v2, 32, v153
	v_bfe_u32 v12, v153, 2, 4
	v_or3_b32 v3, v3, v4, v13
	v_lshrrev_b32_e32 v4, 3, v153
	s_movk_i32 s1, 0x70
	s_add_i32 s8, s6, s0
	v_bitop3_b32 v10, v1, v2, 48 bitop3:0x6c
	v_and_b32_e32 v11, 64, v153
	v_and_or_b32 v5, v4, s1, v12
	s_movk_i32 s1, 0x60
	v_add_u32_e32 v14, 0x2000, v1
	s_bfe_i32 s0, s8, 0x80000
	s_and_b32 s8, s8, 0xf8
	v_or_b32_e32 v2, v10, v11
	v_and_or_b32 v4, v4, s1, v3
	v_lshrrev_b32_e32 v1, 7, v14
	s_movk_i32 s1, 0xf0
	s_sub_i32 s6, s6, s8
	v_lshl_or_b32 v132, v4, 14, v2
	v_and_or_b32 v4, v1, s1, v12
	s_movk_i32 s1, 0xe0
	s_lshl_b32 s7, s7, 3
	s_sext_i32_i16 s0, s0
	s_sext_i32_i8 s6, s6
	v_and_or_b32 v1, v1, s1, v3
	s_lshr_b32 s1, s12, 8
	s_lshr_b32 s0, s0, 3
	s_add_i32 s30, s7, s6
	s_lshr_b32 s10, s12, 6
	s_ashr_i32 s31, s30, 31
	s_bfe_i64 s[8:9], s[0:1], 0x100000
	s_lshl_b32 s44, s10, 10
	s_lshl_b64 s[6:7], s[30:31], 22
	s_lshl_b64 s[8:9], s[8:9], 22
	s_add_u32 s36, s42, s8
	s_addc_u32 s37, s43, s9
	s_add_i32 s31, s44, 0
	s_add_i32 m0, s31, 0x10000
	v_lshl_or_b32 v136, v1, 14, v2
	global_load_lds_dwordx4 v132, s[36:37]
	s_add_i32 m0, s31, 0x12000
	s_add_u32 s8, s36, 0x200000
	global_load_lds_dwordx4 v136, s[36:37]
	s_addc_u32 s9, s37, 0
	s_add_i32 m0, s31, 0x14000
	v_lshl_or_b32 v130, v5, 14, v2
	global_load_lds_dwordx4 v132, s[8:9]
	s_add_i32 m0, s31, 0x16000
	s_add_u32 s34, s40, s6
	s_addc_u32 s35, s41, s7
	s_add_i32 s45, s31, 0x2000
	global_load_lds_dwordx4 v136, s[8:9]
	s_mov_b32 m0, s31
	s_add_u32 s6, s34, 0x200000
	v_lshl_or_b32 v134, v4, 14, v2
	global_load_lds_dwordx4 v130, s[34:35]
	s_mov_b32 m0, s45
	s_addc_u32 s7, s35, 0
	s_add_i32 s46, s31, 0x4000
	global_load_lds_dwordx4 v134, s[34:35]
	s_mov_b32 m0, s46
	s_add_i32 s47, s31, 0x6000
	global_load_lds_dwordx4 v130, s[6:7]
	s_mov_b32 m0, s47
	v_mov_b32_e32 v133, 0
	global_load_lds_dwordx4 v134, s[6:7]
	v_mov_b32_e32 v137, v133
	v_mov_b32_e32 v131, v133
	v_mov_b32_e32 v135, v133
	s_cmp_eq_u32 s1, 1
	s_mov_b32 s48, 0
	v_lshl_add_u64 v[8:9], s[36:37], 0, v[132:133]
	v_lshl_add_u64 v[6:7], s[36:37], 0, v[136:137]
	v_lshl_add_u64 v[2:3], s[34:35], 0, v[130:131]
	s_cselect_b64 s[6:7], -1, 0
	s_mov_b32 s87, s1
	s_cmp_lg_u32 s1, 1
	v_lshl_add_u64 v[4:5], s[34:35], 0, v[134:135]
	s_cbranch_scc1 .LBB0_1180
	s_barrier

.LBB0_1190:
	ds_read_b128 v[156:159], v151
	ds_read_b128 v[160:163], v151 offset:1024
	ds_read_b128 v[164:167], v151 offset:2048
	ds_read_b128 v[168:171], v151 offset:3072
	ds_read_b128 v[172:175], v154
	ds_read_b128 v[176:179], v154 offset:1024
	ds_read_b128 v[180:183], v154 offset:2048
	ds_read_b128 v[184:187], v154 offset:3072
	s_add_u32 s36, s34, 0xffe00080
	s_addc_u32 s37, s35, -1
	s_cmpk_eq_i32 s63, 0x7c
	s_cselect_b32 s39, s25, s37
	s_cselect_b32 s38, s59, s36
	s_cselect_b32 s37, s23, s62
	s_cselect_b32 s36, s60, s61
	v_lshl_add_u64 v[146:147], s[34:35], 0, v[138:139]
	s_add_i32 m0, s31, 0xc000
	ds_read_b128 v[188:191], v155
	ds_read_b128 v[192:195], v155 offset:1024
	ds_read_b128 v[196:199], v155 offset:2048
	ds_read_b128 v[200:203], v155 offset:3072
	ds_read_b128 v[204:207], v155 offset:4096
	ds_read_b128 v[208:211], v155 offset:5120
	ds_read_b128 v[212:215], v155 offset:6144
	ds_read_b128 v[216:219], v155 offset:7168
	global_load_lds_dwordx4 v[146:147], off
	v_lshl_add_u64 v[146:147], s[34:35], 0, v[140:141]
	s_add_i32 m0, s31, 0xe000
	s_nop 0
	global_load_lds_dwordx4 v[146:147], off
	s_cmp_eq_u32 s87, 0
	s_cbranch_scc1 .Lgw10_0a
	s_waitcnt vmcnt(8)
.Lgw10_0a:
	s_waitcnt lgkmcnt(0)
	s_barrier
	s_setprio 1
	s_waitcnt lgkmcnt(0)
	v_mfma_f32_16x16x32_bf16 v[126:129], v[156:159], v[188:191], v[126:129]
	v_mfma_f32_16x16x32_bf16 v[122:125], v[164:167], v[188:191], v[122:125]
	v_mfma_f32_16x16x32_bf16 v[118:121], v[156:159], v[196:199], v[118:121]
	v_mfma_f32_16x16x32_bf16 v[110:113], v[164:167], v[196:199], v[110:113]
	v_mfma_f32_16x16x32_bf16 v[102:105], v[156:159], v[204:207], v[102:105]
	v_mfma_f32_16x16x32_bf16 v[94:97], v[164:167], v[204:207], v[94:97]
	v_mfma_f32_16x16x32_bf16 v[86:89], v[156:159], v[212:215], v[86:89]
	v_mfma_f32_16x16x32_bf16 v[78:81], v[164:167], v[212:215], v[78:81]
	v_mfma_f32_16x16x32_bf16 v[126:129], v[160:163], v[192:195], v[126:129]
	v_mfma_f32_16x16x32_bf16 v[122:125], v[168:171], v[192:195], v[122:125]
	v_mfma_f32_16x16x32_bf16 v[118:121], v[160:163], v[200:203], v[118:121]
	v_mfma_f32_16x16x32_bf16 v[110:113], v[168:171], v[200:203], v[110:113]
	v_mfma_f32_16x16x32_bf16 v[102:105], v[160:163], v[208:211], v[102:105]
	v_mfma_f32_16x16x32_bf16 v[94:97], v[168:171], v[208:211], v[94:97]
	v_mfma_f32_16x16x32_bf16 v[86:89], v[160:163], v[216:219], v[86:89]
	v_mfma_f32_16x16x32_bf16 v[78:81], v[168:171], v[216:219], v[78:81]
	s_setprio 0
	s_setprio 1
	v_mfma_f32_16x16x32_bf16 v[114:117], v[172:175], v[188:191], v[114:117]
	v_mfma_f32_16x16x32_bf16 v[106:109], v[180:183], v[188:191], v[106:109]
	v_mfma_f32_16x16x32_bf16 v[98:101], v[172:175], v[196:199], v[98:101]
	v_mfma_f32_16x16x32_bf16 v[90:93], v[180:183], v[196:199], v[90:93]
	v_mfma_f32_16x16x32_bf16 v[82:85], v[172:175], v[204:207], v[82:85]
	v_mfma_f32_16x16x32_bf16 v[74:77], v[180:183], v[204:207], v[74:77]
	v_mfma_f32_16x16x32_bf16 v[70:73], v[172:175], v[212:215], v[70:73]
	v_mfma_f32_16x16x32_bf16 v[66:69], v[180:183], v[212:215], v[66:69]
	v_mfma_f32_16x16x32_bf16 v[114:117], v[176:179], v[192:195], v[114:117]
	v_mfma_f32_16x16x32_bf16 v[106:109], v[184:187], v[192:195], v[106:109]
	v_mfma_f32_16x16x32_bf16 v[98:101], v[176:179], v[200:203], v[98:101]
	v_mfma_f32_16x16x32_bf16 v[90:93], v[184:187], v[200:203], v[90:93]
	v_mfma_f32_16x16x32_bf16 v[82:85], v[176:179], v[208:211], v[82:85]
	v_mfma_f32_16x16x32_bf16 v[74:77], v[184:187], v[208:211], v[74:77]
	v_mfma_f32_16x16x32_bf16 v[70:73], v[176:179], v[216:219], v[70:73]
	v_mfma_f32_16x16x32_bf16 v[66:69], v[184:187], v[216:219], v[66:69]
	s_setprio 0
	s_cbranch_scc0 .Lgw10_0b
	s_waitcnt vmcnt(8)
.Lgw10_0b:
	s_barrier
	s_add_i32 s64, s52, s44
	v_lshl_add_u64 v[146:147], s[36:37], 0, v[132:133]
	s_mov_b32 m0, s64
	ds_read_b128 v[188:191], v155 offset:16384
	ds_read_b128 v[192:195], v155 offset:17408
	ds_read_b128 v[196:199], v155 offset:18432
	ds_read_b128 v[200:203], v155 offset:19456
	ds_read_b128 v[204:207], v155 offset:20480
	ds_read_b128 v[208:211], v155 offset:21504
	ds_read_b128 v[212:215], v155 offset:22528
	ds_read_b128 v[216:219], v155 offset:23552
	global_load_lds_dwordx4 v[146:147], off
	s_add_i32 m0, s64, 0x2000
	s_add_u32 s64, s36, 0x200000
	v_lshl_add_u64 v[220:221], s[36:37], 0, v[136:137]
	s_addc_u32 s65, s37, 0
	s_add_i32 s66, s53, s44
	global_load_lds_dwordx4 v[220:221], off
	v_lshl_add_u64 v[222:223], s[64:65], 0, v[132:133]
	s_mov_b32 m0, s66
	v_lshl_add_u64 v[224:225], s[38:39], 0, v[134:135]
	global_load_lds_dwordx4 v[222:223], off
	v_lshl_add_u64 v[222:223], s[64:65], 0, v[136:137]
	s_add_i32 m0, s66, 0x2000
	s_nop 0
	global_load_lds_dwordx4 v[222:223], off
	v_lshl_add_u64 v[222:223], s[38:39], 0, v[130:131]
	s_mov_b32 m0, s31
	s_nop 0
	global_load_lds_dwordx4 v[222:223], off
	s_mov_b32 m0, s45
	s_nop 0
	global_load_lds_dwordx4 v[224:225], off
	s_cmp_eq_u32 s87, 0
	s_cbranch_scc1 .Lgw10_1a
	s_waitcnt vmcnt(8)
.Lgw10_1a:
	s_waitcnt lgkmcnt(0)
	s_barrier
	s_setprio 1
	s_waitcnt lgkmcnt(0)
	v_mfma_f32_16x16x32_bf16 v[62:65], v[156:159], v[188:191], v[62:65]
	v_mfma_f32_16x16x32_bf16 v[58:61], v[164:167], v[188:191], v[58:61]
	v_mfma_f32_16x16x32_bf16 v[54:57], v[156:159], v[196:199], v[54:57]
	v_mfma_f32_16x16x32_bf16 v[46:49], v[164:167], v[196:199], v[46:49]
	v_mfma_f32_16x16x32_bf16 v[38:41], v[156:159], v[204:207], v[38:41]
	v_mfma_f32_16x16x32_bf16 v[30:33], v[164:167], v[204:207], v[30:33]
	v_mfma_f32_16x16x32_bf16 v[22:25], v[156:159], v[212:215], v[22:25]
	v_mfma_f32_16x16x32_bf16 v[14:17], v[164:167], v[212:215], v[14:17]
	v_mfma_f32_16x16x32_bf16 v[62:65], v[160:163], v[192:195], v[62:65]
	v_mfma_f32_16x16x32_bf16 v[58:61], v[168:171], v[192:195], v[58:61]
	v_mfma_f32_16x16x32_bf16 v[54:57], v[160:163], v[200:203], v[54:57]
	v_mfma_f32_16x16x32_bf16 v[46:49], v[168:171], v[200:203], v[46:49]
	v_mfma_f32_16x16x32_bf16 v[38:41], v[160:163], v[208:211], v[38:41]
	v_mfma_f32_16x16x32_bf16 v[30:33], v[168:171], v[208:211], v[30:33]
	v_mfma_f32_16x16x32_bf16 v[22:25], v[160:163], v[216:219], v[22:25]
	v_mfma_f32_16x16x32_bf16 v[14:17], v[168:171], v[216:219], v[14:17]
	s_setprio 0
	s_setprio 1
	v_mfma_f32_16x16x32_bf16 v[50:53], v[172:175], v[188:191], v[50:53]
	v_mfma_f32_16x16x32_bf16 v[42:45], v[180:183], v[188:191], v[42:45]
	v_mfma_f32_16x16x32_bf16 v[34:37], v[172:175], v[196:199], v[34:37]
	v_mfma_f32_16x16x32_bf16 v[26:29], v[180:183], v[196:199], v[26:29]
	v_mfma_f32_16x16x32_bf16 v[18:21], v[172:175], v[204:207], v[18:21]
	v_mfma_f32_16x16x32_bf16 v[10:13], v[180:183], v[204:207], v[10:13]
	v_mfma_f32_16x16x32_bf16 v[6:9], v[172:175], v[212:215], v[6:9]
	v_mfma_f32_16x16x32_bf16 v[2:5], v[180:183], v[212:215], v[2:5]
	v_mfma_f32_16x16x32_bf16 v[50:53], v[176:179], v[192:195], v[50:53]
	v_mfma_f32_16x16x32_bf16 v[42:45], v[184:187], v[192:195], v[42:45]
	v_mfma_f32_16x16x32_bf16 v[34:37], v[176:179], v[200:203], v[34:37]
	v_mfma_f32_16x16x32_bf16 v[26:29], v[184:187], v[200:203], v[26:29]
	v_mfma_f32_16x16x32_bf16 v[18:21], v[176:179], v[208:211], v[18:21]
	v_mfma_f32_16x16x32_bf16 v[10:13], v[184:187], v[208:211], v[10:13]
	v_mfma_f32_16x16x32_bf16 v[6:9], v[176:179], v[216:219], v[6:9]
	v_mfma_f32_16x16x32_bf16 v[2:5], v[184:187], v[216:219], v[2:5]
	s_setprio 0
	s_cbranch_scc0 .Lgw10_1b
	s_waitcnt vmcnt(8)
.Lgw10_1b:
	s_barrier
	s_add_i32 s64, 0, 0x18000
	s_add_i32 s65, 0, 0x1c000
	v_add_u32_e32 v168, s64, v149
	v_add_u32_e32 v184, s65, v149
	ds_read_b128 v[156:159], v168
	ds_read_b128 v[160:163], v168 offset:1024
	ds_read_b128 v[164:167], v168 offset:2048
	ds_read_b128 v[168:171], v168 offset:3072
	ds_read_b128 v[172:175], v184
	ds_read_b128 v[176:179], v184 offset:1024
	ds_read_b128 v[180:183], v184 offset:2048
	ds_read_b128 v[184:187], v184 offset:3072
	s_add_u32 s38, s38, 0x200000
	s_addc_u32 s39, s39, 0
	s_mov_b32 m0, s46
	v_lshl_add_u64 v[226:227], s[38:39], 0, v[130:131]
	ds_read_b128 v[188:191], v155 offset:32768
	ds_read_b128 v[192:195], v155 offset:33792
	ds_read_b128 v[196:199], v155 offset:34816
	ds_read_b128 v[200:203], v155 offset:35840
	ds_read_b128 v[204:207], v155 offset:36864
	ds_read_b128 v[208:211], v155 offset:37888
	ds_read_b128 v[212:215], v155 offset:38912
	ds_read_b128 v[216:219], v155 offset:39936
	global_load_lds_dwordx4 v[226:227], off
	v_lshl_add_u64 v[226:227], s[38:39], 0, v[134:135]
	s_mov_b32 m0, s47
	s_nop 0
	global_load_lds_dwordx4 v[226:227], off
	s_cmp_eq_u32 s87, 0
	s_cbranch_scc1 .Lgw10_2a
	s_waitcnt vmcnt(8)

.Lgw10_2b:
	s_barrier
	s_add_i32 s38, s64, s44
	v_lshl_add_u64 v[146:147], v[146:147], 0, s[10:11]
	s_mov_b32 m0, s38
	ds_read_b128 v[188:191], v155 offset:49152
	ds_read_b128 v[192:195], v155 offset:50176
	ds_read_b128 v[196:199], v155 offset:51200
	ds_read_b128 v[200:203], v155 offset:52224
	ds_read_b128 v[204:207], v155 offset:53248
	ds_read_b128 v[208:211], v155 offset:54272
	ds_read_b128 v[212:215], v155 offset:55296
	ds_read_b128 v[216:219], v155 offset:56320
	global_load_lds_dwordx4 v[146:147], off
	s_add_i32 m0, s38, 0x2000
	s_add_u32 s36, s36, 0x200080
	v_lshl_add_u64 v[146:147], v[220:221], 0, s[10:11]
	s_addc_u32 s37, s37, 0
	s_add_i32 s38, s65, s44
	global_load_lds_dwordx4 v[146:147], off
	v_lshl_add_u64 v[146:147], s[36:37], 0, v[132:133]
	s_mov_b32 m0, s38
	s_nop 0
	global_load_lds_dwordx4 v[146:147], off
	v_lshl_add_u64 v[146:147], s[36:37], 0, v[136:137]
	s_add_i32 m0, s38, 0x2000
	s_nop 0
	global_load_lds_dwordx4 v[146:147], off
	v_lshl_add_u64 v[146:147], v[222:223], 0, s[10:11]
	s_mov_b32 m0, s49
	s_nop 0
	global_load_lds_dwordx4 v[146:147], off
	v_lshl_add_u64 v[146:147], v[224:225], 0, s[10:11]
	s_mov_b32 m0, s50
	s_nop 0
	global_load_lds_dwordx4 v[146:147], off
	s_cmp_eq_u32 s87, 0
	s_cbranch_scc1 .Lgw10_3a
	s_waitcnt vmcnt(8)

.Lgw10_3b:
	s_barrier
	s_add_i32 s63, s63, 2
	s_add_u32 s34, s34, 0x100
	s_addc_u32 s35, s35, 0
	s_add_u32 s61, s61, 0x100
	s_addc_u32 s62, s62, 0
	s_cmpk_gt_u32 s63, 0x7d
	s_cbranch_scc0 .LBB0_1190
	s_and_b64 vcc, exec, s[12:13]
	s_cbranch_vccz .LBB0_1193
	s_barrier
